# adaLN item staging (silu of conditioning rows into LDS): 24 per-thread loads issued together, counted vmcnt; on top of v46
# speedup vs baseline: 1.0037x; 1.0037x over previous
; DI float sigmf(float x) { return __builtin_amdgcn_rcpf(1.f + __expf(-x)); }
; DI float siluf(float x) { return x * sigmf(x); }
; DI void phase_ada_item(CP p, const Ptrs& w, int l, int item, int ksplit, float* sm) {
;     ...
;   __syncthreads();
;   for (int e = tid; e < 3 * 2048; e += 256) {
;     int v = e >> 11, k = e & 2047;
;     float x = v < 2 ? p.in[1][v * 2048 + k] : p.in[3][k];
;     act[e] = siluf(x);
;   }
.LBB0_36:
	s_waitcnt vmcnt(5)
	v_mov_b32_e32 v8, v214
	s_movk_i32 s12, 0x1800
	s_waitcnt lgkmcnt(0)
	v_cmp_gt_i32_e32 vcc, s12, v8
	s_waitcnt vmcnt(3)
	v_lshlrev_b32_e32 v18, 2, v8
	s_barrier
	s_and_saveexec_b64 s[12:13], vcc
	s_movk_i32 s17, 0x1000
	s_mov_b64 s[40:41], 0x400
	s_movk_i32 s42, 0x16ff
	s_cbranch_execz .LBB0_39
	s_load_dwordx2 s[14:15], s[2:3], 0x8
	s_load_dwordx2 s[38:39], s[2:3], 0x18
	s_waitcnt lgkmcnt(0)
	s_mov_b64 s[100:101], s[14:15]
	global_load_dword v96, v18, s[100:101]
	global_load_dword v97, v18, s[100:101] offset:1024
	global_load_dword v98, v18, s[100:101] offset:2048
	global_load_dword v99, v18, s[100:101] offset:3072
	s_add_u32 s100, s100, 0x1000
	s_addc_u32 s101, s101, 0
	global_load_dword v100, v18, s[100:101]
	global_load_dword v101, v18, s[100:101] offset:1024
	global_load_dword v102, v18, s[100:101] offset:2048
	global_load_dword v103, v18, s[100:101] offset:3072
	s_add_u32 s100, s100, 0x1000
	s_addc_u32 s101, s101, 0
	global_load_dword v104, v18, s[100:101]
	global_load_dword v105, v18, s[100:101] offset:1024
	global_load_dword v106, v18, s[100:101] offset:2048
	global_load_dword v107, v18, s[100:101] offset:3072
	s_add_u32 s100, s100, 0x1000
	s_addc_u32 s101, s101, 0
	global_load_dword v108, v18, s[100:101]
	global_load_dword v109, v18, s[100:101] offset:1024
	global_load_dword v110, v18, s[100:101] offset:2048
	global_load_dword v111, v18, s[100:101] offset:3072
	s_mov_b64 s[100:101], s[38:39]
	global_load_dword v112, v18, s[100:101]
	global_load_dword v113, v18, s[100:101] offset:1024
	global_load_dword v114, v18, s[100:101] offset:2048
	global_load_dword v115, v18, s[100:101] offset:3072
	s_add_u32 s100, s100, 0x1000
	s_addc_u32 s101, s101, 0
	global_load_dword v116, v18, s[100:101]
	global_load_dword v117, v18, s[100:101] offset:1024
	global_load_dword v118, v18, s[100:101] offset:2048
	global_load_dword v119, v18, s[100:101] offset:3072
	s_waitcnt vmcnt(23)
	v_mul_f32_e32 v5, 0xbfb8aa3b, v96
	v_exp_f32_e32 v5, v5
	s_nop 0
	v_add_f32_e32 v5, 1.0, v5
	v_rcp_f32_e32 v5, v5
	s_nop 0
	v_mul_f32_e32 v4, v96, v5
	ds_write_b32 v18, v4
	s_waitcnt vmcnt(22)
	v_mul_f32_e32 v5, 0xbfb8aa3b, v97
	v_exp_f32_e32 v5, v5
	s_nop 0
	v_add_f32_e32 v5, 1.0, v5
	v_rcp_f32_e32 v5, v5
	s_nop 0
	v_mul_f32_e32 v4, v97, v5
	ds_write_b32 v18, v4 offset:1024
	s_waitcnt vmcnt(21)
	v_mul_f32_e32 v5, 0xbfb8aa3b, v98
	v_exp_f32_e32 v5, v5
	s_nop 0
	v_add_f32_e32 v5, 1.0, v5
	v_rcp_f32_e32 v5, v5
	s_nop 0
	v_mul_f32_e32 v4, v98, v5
	ds_write_b32 v18, v4 offset:2048
	s_waitcnt vmcnt(20)
	v_mul_f32_e32 v5, 0xbfb8aa3b, v99
	v_exp_f32_e32 v5, v5
	s_nop 0
	v_add_f32_e32 v5, 1.0, v5
	v_rcp_f32_e32 v5, v5
	s_nop 0
	v_mul_f32_e32 v4, v99, v5
	ds_write_b32 v18, v4 offset:3072
	s_waitcnt vmcnt(19)
	v_mul_f32_e32 v5, 0xbfb8aa3b, v100
	v_exp_f32_e32 v5, v5
	s_nop 0
	v_add_f32_e32 v5, 1.0, v5
	v_rcp_f32_e32 v5, v5
	s_nop 0
	v_mul_f32_e32 v4, v100, v5
	ds_write_b32 v18, v4 offset:4096
	s_waitcnt vmcnt(18)
	v_mul_f32_e32 v5, 0xbfb8aa3b, v101
	v_exp_f32_e32 v5, v5
	s_nop 0
	v_add_f32_e32 v5, 1.0, v5
	v_rcp_f32_e32 v5, v5
	s_nop 0
	v_mul_f32_e32 v4, v101, v5
	ds_write_b32 v18, v4 offset:5120
	s_waitcnt vmcnt(17)
	v_mul_f32_e32 v5, 0xbfb8aa3b, v102
	v_exp_f32_e32 v5, v5
	s_nop 0
	v_add_f32_e32 v5, 1.0, v5
	v_rcp_f32_e32 v5, v5
	s_nop 0
	v_mul_f32_e32 v4, v102, v5
	ds_write_b32 v18, v4 offset:6144
	s_waitcnt vmcnt(16)
	v_mul_f32_e32 v5, 0xbfb8aa3b, v103
	v_exp_f32_e32 v5, v5
	s_nop 0
	v_add_f32_e32 v5, 1.0, v5
	v_rcp_f32_e32 v5, v5
	s_nop 0
	v_mul_f32_e32 v4, v103, v5
	ds_write_b32 v18, v4 offset:7168
	s_waitcnt vmcnt(15)
	v_mul_f32_e32 v5, 0xbfb8aa3b, v104
	v_exp_f32_e32 v5, v5
	s_nop 0
	v_add_f32_e32 v5, 1.0, v5
	v_rcp_f32_e32 v5, v5
	s_nop 0
	v_mul_f32_e32 v4, v104, v5
	ds_write_b32 v18, v4 offset:8192
	s_waitcnt vmcnt(14)
	v_mul_f32_e32 v5, 0xbfb8aa3b, v105
	v_exp_f32_e32 v5, v5
	s_nop 0
	v_add_f32_e32 v5, 1.0, v5
	v_rcp_f32_e32 v5, v5
	s_nop 0
	v_mul_f32_e32 v4, v105, v5
	ds_write_b32 v18, v4 offset:9216
	s_waitcnt vmcnt(13)
	v_mul_f32_e32 v5, 0xbfb8aa3b, v106
	v_exp_f32_e32 v5, v5
	s_nop 0
	v_add_f32_e32 v5, 1.0, v5
	v_rcp_f32_e32 v5, v5
	s_nop 0
	v_mul_f32_e32 v4, v106, v5
	ds_write_b32 v18, v4 offset:10240
	s_waitcnt vmcnt(12)
	v_mul_f32_e32 v5, 0xbfb8aa3b, v107
	v_exp_f32_e32 v5, v5
	s_nop 0
	v_add_f32_e32 v5, 1.0, v5
	v_rcp_f32_e32 v5, v5
	s_nop 0
	v_mul_f32_e32 v4, v107, v5
	ds_write_b32 v18, v4 offset:11264
	s_waitcnt vmcnt(11)
	v_mul_f32_e32 v5, 0xbfb8aa3b, v108
	v_exp_f32_e32 v5, v5
	s_nop 0
	v_add_f32_e32 v5, 1.0, v5
	v_rcp_f32_e32 v5, v5
	s_nop 0
	v_mul_f32_e32 v4, v108, v5
	ds_write_b32 v18, v4 offset:12288
	s_waitcnt vmcnt(10)
	v_mul_f32_e32 v5, 0xbfb8aa3b, v109
	v_exp_f32_e32 v5, v5
	s_nop 0
	v_add_f32_e32 v5, 1.0, v5
	v_rcp_f32_e32 v5, v5
	s_nop 0
	v_mul_f32_e32 v4, v109, v5
	ds_write_b32 v18, v4 offset:13312
	s_waitcnt vmcnt(9)
	v_mul_f32_e32 v5, 0xbfb8aa3b, v110
	v_exp_f32_e32 v5, v5
	s_nop 0
	v_add_f32_e32 v5, 1.0, v5
	v_rcp_f32_e32 v5, v5
	s_nop 0
	v_mul_f32_e32 v4, v110, v5
	ds_write_b32 v18, v4 offset:14336
	s_waitcnt vmcnt(8)
	v_mul_f32_e32 v5, 0xbfb8aa3b, v111
	v_exp_f32_e32 v5, v5
	s_nop 0
	v_add_f32_e32 v5, 1.0, v5
	v_rcp_f32_e32 v5, v5
	s_nop 0
	v_mul_f32_e32 v4, v111, v5
	ds_write_b32 v18, v4 offset:15360
	s_waitcnt vmcnt(7)
	v_mul_f32_e32 v5, 0xbfb8aa3b, v112
	v_exp_f32_e32 v5, v5
	s_nop 0
	v_add_f32_e32 v5, 1.0, v5
	v_rcp_f32_e32 v5, v5
	s_nop 0
	v_mul_f32_e32 v4, v112, v5
	ds_write_b32 v18, v4 offset:16384
	s_waitcnt vmcnt(6)
	v_mul_f32_e32 v5, 0xbfb8aa3b, v113
	v_exp_f32_e32 v5, v5
	s_nop 0
	v_add_f32_e32 v5, 1.0, v5
	v_rcp_f32_e32 v5, v5
	s_nop 0
	v_mul_f32_e32 v4, v113, v5
	ds_write_b32 v18, v4 offset:17408
	s_waitcnt vmcnt(5)
	v_mul_f32_e32 v5, 0xbfb8aa3b, v114
	v_exp_f32_e32 v5, v5
	s_nop 0
	v_add_f32_e32 v5, 1.0, v5
	v_rcp_f32_e32 v5, v5
	s_nop 0
	v_mul_f32_e32 v4, v114, v5
	ds_write_b32 v18, v4 offset:18432
	s_waitcnt vmcnt(4)
	v_mul_f32_e32 v5, 0xbfb8aa3b, v115
	v_exp_f32_e32 v5, v5
	s_nop 0
	v_add_f32_e32 v5, 1.0, v5
	v_rcp_f32_e32 v5, v5
	s_nop 0
	v_mul_f32_e32 v4, v115, v5
	ds_write_b32 v18, v4 offset:19456
	s_waitcnt vmcnt(3)
	v_mul_f32_e32 v5, 0xbfb8aa3b, v116
	v_exp_f32_e32 v5, v5
	s_nop 0
	v_add_f32_e32 v5, 1.0, v5
	v_rcp_f32_e32 v5, v5
	s_nop 0
	v_mul_f32_e32 v4, v116, v5
	ds_write_b32 v18, v4 offset:20480
	s_waitcnt vmcnt(2)
	v_mul_f32_e32 v5, 0xbfb8aa3b, v117
	v_exp_f32_e32 v5, v5
	s_nop 0
	v_add_f32_e32 v5, 1.0, v5
	v_rcp_f32_e32 v5, v5
	s_nop 0
	v_mul_f32_e32 v4, v117, v5
	ds_write_b32 v18, v4 offset:21504
	s_waitcnt vmcnt(1)
	v_mul_f32_e32 v5, 0xbfb8aa3b, v118
	v_exp_f32_e32 v5, v5
	s_nop 0
	v_add_f32_e32 v5, 1.0, v5
	v_rcp_f32_e32 v5, v5
	s_nop 0
	v_mul_f32_e32 v4, v118, v5
	ds_write_b32 v18, v4 offset:22528
	s_waitcnt vmcnt(0)
	v_mul_f32_e32 v5, 0xbfb8aa3b, v119
	v_exp_f32_e32 v5, v5
	s_nop 0
	v_add_f32_e32 v5, 1.0, v5
	v_rcp_f32_e32 v5, v5
	s_nop 0
	v_mul_f32_e32 v4, v119, v5
	ds_write_b32 v18, v4 offset:23552

; DI float sigmf(float x) { return __builtin_amdgcn_rcpf(1.f + __expf(-x)); }
; DI float siluf(float x) { return x * sigmf(x); }
; DI void phase_ada_item(CP p, const Ptrs& w, int l, int item, int ksplit, float* sm) {
;     ...
;   __syncthreads();
;   for (int e = tid; e < 3 * 2048; e += 256) {
;     int v = e >> 11, k = e & 2047;
;     float x = v < 2 ? p.in[1][v * 2048 + k] : p.in[3][k];
;     act[e] = siluf(x);
;   }
.LBB0_241:
	s_or_b64 exec, exec, s[38:39]
	s_waitcnt lgkmcnt(0)
	s_barrier
	ds_read_b32 v0, v220
	s_movk_i32 s17, 0x5f
	s_mov_b64 s[38:39], -1
	s_waitcnt lgkmcnt(0)
	v_cmp_lt_i32_e32 vcc, s17, v0
	v_readfirstlane_b32 s16, v0
	s_cbranch_vccnz .LBB0_236
	s_waitcnt vmcnt(5)
	v_mov_b32_e32 v8, v214
	s_movk_i32 s17, 0x1800
	s_nop 0
	v_cmp_gt_i32_e32 vcc, s17, v8
	s_waitcnt vmcnt(3)
	v_lshlrev_b32_e32 v18, 2, v8
	s_barrier
	s_and_saveexec_b64 s[38:39], vcc
	s_movk_i32 s17, 0x1000
	s_mov_b64 s[42:43], 0x400
	s_movk_i32 s44, 0x16ff
	s_cbranch_execz .LBB0_245
	s_mov_b64 s[100:101], s[12:13]
	global_load_dword v96, v18, s[100:101]
	global_load_dword v97, v18, s[100:101] offset:1024
	global_load_dword v98, v18, s[100:101] offset:2048
	global_load_dword v99, v18, s[100:101] offset:3072
	s_add_u32 s100, s100, 0x1000
	s_addc_u32 s101, s101, 0
	global_load_dword v100, v18, s[100:101]
	global_load_dword v101, v18, s[100:101] offset:1024
	global_load_dword v102, v18, s[100:101] offset:2048
	global_load_dword v103, v18, s[100:101] offset:3072
	s_add_u32 s100, s100, 0x1000
	s_addc_u32 s101, s101, 0
	global_load_dword v104, v18, s[100:101]
	global_load_dword v105, v18, s[100:101] offset:1024
	global_load_dword v106, v18, s[100:101] offset:2048
	global_load_dword v107, v18, s[100:101] offset:3072
	s_add_u32 s100, s100, 0x1000
	s_addc_u32 s101, s101, 0
	global_load_dword v108, v18, s[100:101]
	global_load_dword v109, v18, s[100:101] offset:1024
	global_load_dword v110, v18, s[100:101] offset:2048
	global_load_dword v111, v18, s[100:101] offset:3072
	s_mov_b64 s[100:101], s[14:15]
	global_load_dword v112, v18, s[100:101]
	global_load_dword v113, v18, s[100:101] offset:1024
	global_load_dword v114, v18, s[100:101] offset:2048
	global_load_dword v115, v18, s[100:101] offset:3072
	s_add_u32 s100, s100, 0x1000
	s_addc_u32 s101, s101, 0
	global_load_dword v116, v18, s[100:101]
	global_load_dword v117, v18, s[100:101] offset:1024
	global_load_dword v118, v18, s[100:101] offset:2048
	global_load_dword v119, v18, s[100:101] offset:3072
	s_waitcnt vmcnt(23)
	v_mul_f32_e32 v5, 0xbfb8aa3b, v96
	v_exp_f32_e32 v5, v5
	s_nop 0
	v_add_f32_e32 v5, 1.0, v5
	v_rcp_f32_e32 v5, v5
	s_nop 0
	v_mul_f32_e32 v4, v96, v5
	ds_write_b32 v18, v4
	s_waitcnt vmcnt(22)
	v_mul_f32_e32 v5, 0xbfb8aa3b, v97
	v_exp_f32_e32 v5, v5
	s_nop 0
	v_add_f32_e32 v5, 1.0, v5
	v_rcp_f32_e32 v5, v5
	s_nop 0
	v_mul_f32_e32 v4, v97, v5
	ds_write_b32 v18, v4 offset:1024
	s_waitcnt vmcnt(21)
	v_mul_f32_e32 v5, 0xbfb8aa3b, v98
	v_exp_f32_e32 v5, v5
	s_nop 0
	v_add_f32_e32 v5, 1.0, v5
	v_rcp_f32_e32 v5, v5
	s_nop 0
	v_mul_f32_e32 v4, v98, v5
	ds_write_b32 v18, v4 offset:2048
	s_waitcnt vmcnt(20)
	v_mul_f32_e32 v5, 0xbfb8aa3b, v99
	v_exp_f32_e32 v5, v5
	s_nop 0
	v_add_f32_e32 v5, 1.0, v5
	v_rcp_f32_e32 v5, v5
	s_nop 0
	v_mul_f32_e32 v4, v99, v5
	ds_write_b32 v18, v4 offset:3072
	s_waitcnt vmcnt(19)
	v_mul_f32_e32 v5, 0xbfb8aa3b, v100
	v_exp_f32_e32 v5, v5
	s_nop 0
	v_add_f32_e32 v5, 1.0, v5
	v_rcp_f32_e32 v5, v5
	s_nop 0
	v_mul_f32_e32 v4, v100, v5
	ds_write_b32 v18, v4 offset:4096
	s_waitcnt vmcnt(18)
	v_mul_f32_e32 v5, 0xbfb8aa3b, v101
	v_exp_f32_e32 v5, v5
	s_nop 0
	v_add_f32_e32 v5, 1.0, v5
	v_rcp_f32_e32 v5, v5
	s_nop 0
	v_mul_f32_e32 v4, v101, v5
	ds_write_b32 v18, v4 offset:5120
	s_waitcnt vmcnt(17)
	v_mul_f32_e32 v5, 0xbfb8aa3b, v102
	v_exp_f32_e32 v5, v5
	s_nop 0
	v_add_f32_e32 v5, 1.0, v5
	v_rcp_f32_e32 v5, v5
	s_nop 0
	v_mul_f32_e32 v4, v102, v5
	ds_write_b32 v18, v4 offset:6144
	s_waitcnt vmcnt(16)
	v_mul_f32_e32 v5, 0xbfb8aa3b, v103
	v_exp_f32_e32 v5, v5
	s_nop 0
	v_add_f32_e32 v5, 1.0, v5
	v_rcp_f32_e32 v5, v5
	s_nop 0
	v_mul_f32_e32 v4, v103, v5
	ds_write_b32 v18, v4 offset:7168
	s_waitcnt vmcnt(15)
	v_mul_f32_e32 v5, 0xbfb8aa3b, v104
	v_exp_f32_e32 v5, v5
	s_nop 0
	v_add_f32_e32 v5, 1.0, v5
	v_rcp_f32_e32 v5, v5
	s_nop 0
	v_mul_f32_e32 v4, v104, v5
	ds_write_b32 v18, v4 offset:8192
	s_waitcnt vmcnt(14)
	v_mul_f32_e32 v5, 0xbfb8aa3b, v105
	v_exp_f32_e32 v5, v5
	s_nop 0
	v_add_f32_e32 v5, 1.0, v5
	v_rcp_f32_e32 v5, v5
	s_nop 0
	v_mul_f32_e32 v4, v105, v5
	ds_write_b32 v18, v4 offset:9216
	s_waitcnt vmcnt(13)
	v_mul_f32_e32 v5, 0xbfb8aa3b, v106
	v_exp_f32_e32 v5, v5
	s_nop 0
	v_add_f32_e32 v5, 1.0, v5
	v_rcp_f32_e32 v5, v5
	s_nop 0
	v_mul_f32_e32 v4, v106, v5
	ds_write_b32 v18, v4 offset:10240
	s_waitcnt vmcnt(12)
	v_mul_f32_e32 v5, 0xbfb8aa3b, v107
	v_exp_f32_e32 v5, v5
	s_nop 0
	v_add_f32_e32 v5, 1.0, v5
	v_rcp_f32_e32 v5, v5
	s_nop 0
	v_mul_f32_e32 v4, v107, v5
	ds_write_b32 v18, v4 offset:11264
	s_waitcnt vmcnt(11)
	v_mul_f32_e32 v5, 0xbfb8aa3b, v108
	v_exp_f32_e32 v5, v5
	s_nop 0
	v_add_f32_e32 v5, 1.0, v5
	v_rcp_f32_e32 v5, v5
	s_nop 0
	v_mul_f32_e32 v4, v108, v5
	ds_write_b32 v18, v4 offset:12288
	s_waitcnt vmcnt(10)
	v_mul_f32_e32 v5, 0xbfb8aa3b, v109
	v_exp_f32_e32 v5, v5
	s_nop 0
	v_add_f32_e32 v5, 1.0, v5
	v_rcp_f32_e32 v5, v5
	s_nop 0
	v_mul_f32_e32 v4, v109, v5
	ds_write_b32 v18, v4 offset:13312
	s_waitcnt vmcnt(9)
	v_mul_f32_e32 v5, 0xbfb8aa3b, v110
	v_exp_f32_e32 v5, v5
	s_nop 0
	v_add_f32_e32 v5, 1.0, v5
	v_rcp_f32_e32 v5, v5
	s_nop 0
	v_mul_f32_e32 v4, v110, v5
	ds_write_b32 v18, v4 offset:14336
	s_waitcnt vmcnt(8)
	v_mul_f32_e32 v5, 0xbfb8aa3b, v111
	v_exp_f32_e32 v5, v5
	s_nop 0
	v_add_f32_e32 v5, 1.0, v5
	v_rcp_f32_e32 v5, v5
	s_nop 0
	v_mul_f32_e32 v4, v111, v5
	ds_write_b32 v18, v4 offset:15360
	s_waitcnt vmcnt(7)
	v_mul_f32_e32 v5, 0xbfb8aa3b, v112
	v_exp_f32_e32 v5, v5
	s_nop 0
	v_add_f32_e32 v5, 1.0, v5
	v_rcp_f32_e32 v5, v5
	s_nop 0
	v_mul_f32_e32 v4, v112, v5
	ds_write_b32 v18, v4 offset:16384
	s_waitcnt vmcnt(6)
	v_mul_f32_e32 v5, 0xbfb8aa3b, v113
	v_exp_f32_e32 v5, v5
	s_nop 0
	v_add_f32_e32 v5, 1.0, v5
	v_rcp_f32_e32 v5, v5
	s_nop 0
	v_mul_f32_e32 v4, v113, v5
	ds_write_b32 v18, v4 offset:17408
	s_waitcnt vmcnt(5)
	v_mul_f32_e32 v5, 0xbfb8aa3b, v114
	v_exp_f32_e32 v5, v5
	s_nop 0
	v_add_f32_e32 v5, 1.0, v5
	v_rcp_f32_e32 v5, v5
	s_nop 0
	v_mul_f32_e32 v4, v114, v5
	ds_write_b32 v18, v4 offset:18432
	s_waitcnt vmcnt(4)
	v_mul_f32_e32 v5, 0xbfb8aa3b, v115
	v_exp_f32_e32 v5, v5
	s_nop 0
	v_add_f32_e32 v5, 1.0, v5
	v_rcp_f32_e32 v5, v5
	s_nop 0
	v_mul_f32_e32 v4, v115, v5
	ds_write_b32 v18, v4 offset:19456
	s_waitcnt vmcnt(3)
	v_mul_f32_e32 v5, 0xbfb8aa3b, v116
	v_exp_f32_e32 v5, v5
	s_nop 0
	v_add_f32_e32 v5, 1.0, v5
	v_rcp_f32_e32 v5, v5
	s_nop 0
	v_mul_f32_e32 v4, v116, v5
	ds_write_b32 v18, v4 offset:20480
	s_waitcnt vmcnt(2)
	v_mul_f32_e32 v5, 0xbfb8aa3b, v117
	v_exp_f32_e32 v5, v5
	s_nop 0
	v_add_f32_e32 v5, 1.0, v5
	v_rcp_f32_e32 v5, v5
	s_nop 0
	v_mul_f32_e32 v4, v117, v5
	ds_write_b32 v18, v4 offset:21504
	s_waitcnt vmcnt(1)
	v_mul_f32_e32 v5, 0xbfb8aa3b, v118
	v_exp_f32_e32 v5, v5
	s_nop 0
	v_add_f32_e32 v5, 1.0, v5
	v_rcp_f32_e32 v5, v5
	s_nop 0
	v_mul_f32_e32 v4, v118, v5
	ds_write_b32 v18, v4 offset:22528
	s_waitcnt vmcnt(0)
	v_mul_f32_e32 v5, 0xbfb8aa3b, v119
	v_exp_f32_e32 v5, v5
	s_nop 0
	v_add_f32_e32 v5, 1.0, v5
	v_rcp_f32_e32 v5, v5
	s_nop 0
	v_mul_f32_e32 v4, v119, v5
	ds_write_b32 v18, v4 offset:23552
